# lru1: conservative waits in the conv-window loads removed, gate-weight rows loaded at item start, lru item index rotated; residual row loads hoisted above the LDS write phase
# speedup vs baseline: 1.0817x; 1.0120x over previous
; DI int TID() { int t = threadIdx.x & 255; asm volatile("" : "+v"(t)); return t; }
; #define VB() (2 * B + (TID512() >> 8))
; #define HS() (smem + (TID512() >> 8) * HALF_LDS)
; DI void lru1_item(const Params& p, int l, int it, char* smem) {
;   const int ci = it >> 3, nb = it & 7;
;   bool isS; int b, row0, Lc, t0;
;   lru_decode(ci, isS, b, row0, Lc, t0);
;   const int tid = TID(), lane = tid & 63, wid = tid >> 6, fr = lane & 15, fq = lane >> 4;
;   u16* xcs = (u16*)smem;
;   u16* was = (u16*)(smem + 9216);
;   u16* wxs = (u16*)(smem + 2 * 9216);
;   float* as_ = (float*)(smem + 3 * 9216);
;   float* us_ = (float*)(smem + 3 * 9216 + 16384);
;   float* segP = (float*)(smem + 3 * 9216 + 32768);
;   float* segH = (float*)(smem + 3 * 9216 + 32768 + 1024);
;   const float* LX = (const float*)(p.ws + O_LX);
;   const u16* Wl = (const u16*)(p.ws + O_WT) + (size_t)l * W_LAYER;
;   const int i = tid & 63, tq = tid >> 6, ch = nb * 64 + i;
; __global__ void __launch_bounds__(512, 2) mega(Params p) {
;     ...
;     if (ONLY < 0 || ONLY == 14) for (int it = VB(); it < L1_ITEMS; it += vG) lru1_item(p, l, it, HS());
.LBB0_1451:
	s_or_b64 exec, exec, s[4:5]
	v_mov_b32_e32 v0, v184
	v_readlane_b32 s4, v251, 5
	v_ashrrev_i32_e32 v0, 8, v0
	v_readlane_b32 s5, v251, 6
	v_add_u32_e32 v2, s4, v0
	v_add_u32_e32 v2, 0x1c0, v2
	v_and_b32_e32 v2, 0x1ff, v2
	v_cmp_gt_i32_e32 vcc, s2, v2
	s_mov_b64 s[4:5], exec
	v_writelane_b32 v254, s4, 62
	s_nop 1
	v_writelane_b32 v254, s5, 63
	s_and_b64 s[4:5], s[4:5], vcc
	s_mov_b64 exec, s[4:5]
	s_cbranch_execz .LBB0_1716
	v_readlane_b32 s8, v254, 39
	v_readlane_b32 s9, v254, 40
	s_lshl_b64 s[4:5], s[8:9], 13
	v_readlane_b32 s28, v254, 9
	v_readlane_b32 s29, v254, 10
	s_add_u32 s26, s28, s4
	s_addc_u32 s27, s29, s5
	v_readlane_b32 s4, v254, 60
	v_readlane_b32 s5, v254, 61
	v_readlane_b32 s30, v254, 11
	s_lshl_b64 s[6:7], s[4:5], 2
	v_readlane_b32 s31, v254, 12
	s_add_u32 s28, s30, s6
	s_addc_u32 s29, s31, s7
	s_lshl_b64 s[30:31], s[8:9], 4
	v_readlane_b32 s4, v254, 57
	s_add_u32 s34, s4, 0x2910000
	v_readlane_b32 s5, v254, 58
	s_addc_u32 s35, s5, 0
	s_add_u32 s36, s4, 0x2920000
	s_addc_u32 s37, s5, 0
	v_readlane_b32 s4, v254, 7
	v_readlane_b32 s5, v254, 8
	s_add_u32 s12, s4, s6
	s_addc_u32 s13, s5, s7
	v_readlane_b32 s8, v254, 13
	v_readlane_b32 s9, v254, 14
	s_add_u32 s4, s8, s6
	v_readlane_b32 s10, v254, 15
	s_addc_u32 s5, s9, s7
	v_readlane_b32 s11, v254, 16
	s_add_u32 s6, s10, s6
	s_addc_u32 s7, s11, s7
	s_mov_b64 s[8:9], 0
	s_branch .LBB0_1454

; DI void lru1_item(const Params& p, int l, int it, char* smem) {
;     ...
;   const int i = tid & 63, tq = tid >> 6, ch = nb * 64 + i;
;   __syncthreads();
;   {
;     const float* cw = p.in[15] + (size_t)l * 4 * 512 + ch;
;     const float w0 = cw[0], w1 = cw[512], w2 = cw[1024], w3 = cw[1536], cb = p.in[16][(size_t)l * 512 + ch];
;     const float* buf = isS ? p.in[5] + ((size_t)l * SBT + b) * 3 * 512 + ch : nullptr;
;     float x[19];
; #pragma unroll
;     for (int j = 0; j < 19; ++j) {
;       const int tl = tq * 16 - 3 + j;
;       const int tt = t0 + tl;
;       float v = 0.f;
;       if (tl < Lc) {
;         if (tt >= 0) v = LX[(size_t)(row0 + tl) * 512 + ch];
;         else if (isS) v = buf[(3 + tt) * 512];
;       }
;       x[j] = v;
;     }
; #pragma unroll
;     for (int k = 0; k < 16; ++k) {
;       const int t = tq * 16 + k;
;       const float xv = (t < Lc) ? cb + w0 * x[k] + w1 * x[k + 1] + w2 * x[k + 2] + w3 * x[k + 3] : 0.f;
;       xcs[t * LP + i] = f2bf(xv);
;     }
; #pragma unroll
;     for (int k = 0; k < 2; ++k) {
;       const int id = tid + k * 256, r = id >> 3, c8 = id & 7;
;       *(uint4*)(was + r * LP + c8 * 8) = *(const uint4*)(Wl + W_WA + nb * 4096 + r * 64 + c8 * 8);
;       *(uint4*)(wxs + r * LP + c8 * 8) = *(const uint4*)(Wl + W_WX + nb * 4096 + r * 64 + c8 * 8);
.LBB0_1454:
	v_ashrrev_i32_e32 v0, 3, v2
	s_movk_i32 s10, 0x1ff
	v_cmp_lt_i32_e64 s[68:69], s10, v0
	s_movk_i32 s10, 0x200
	v_mov_b32_e32 v19, v184
	v_cmp_gt_i32_e32 vcc, s10, v0
	s_and_saveexec_b64 s[10:11], vcc
	s_xor_b64 s[10:11], exec, s[10:11]
	v_lshlrev_b32_e32 v1, 6, v0
	v_ashrrev_i32_e32 v8, 10, v2
	v_and_b32_e32 v13, 0x1fc0, v1
	s_or_saveexec_b64 s[38:39], s[10:11]
	v_mov_b32_e32 v40, 64
	s_xor_b64 exec, exec, s[38:39]
	v_add_u32_e32 v8, 0xfffffe00, v0
	v_mov_b32_e32 v1, 0x8000
	v_lshl_add_u32 v1, v8, 5, v1
	v_mov_b32_e32 v40, 32
	v_mov_b32_e32 v13, 0
	s_or_b64 exec, exec, s[38:39]
	v_and_b32_e32 v10, 7, v2
	v_mov_b32_e32 v43, v185
	v_lshlrev_b32_e32 v14, 6, v10
	v_and_b32_e32 v20, 63, v43
	v_or_b32_e32 v41, v20, v14
	v_lshlrev_b32_e32 v172, 2, v41
	v_lshl_add_u64 v[4:5], s[26:27], 0, v[172:173]
	v_add_co_u32_e32 v4, vcc, 0x1000, v4
	s_waitcnt vmcnt(0) lgkmcnt(0)
	s_barrier
	v_addc_co_u32_e32 v5, vcc, 0, v5, vcc
	global_load_dword v11, v172, s[26:27]
	global_load_dword v15, v172, s[26:27] offset:2048
	global_load_dword v16, v[4:5], off
	global_load_dword v17, v172, s[28:29]
	global_load_dword v18, v[4:5], off offset:2048
	v_lshlrev_b32_e32 v66, 13, v10
	v_mov_b32_e32 v67, v173
	v_lshlrev_b32_e32 v68, 4, v43
	v_and_b32_e32 v68, 0x70, v68
	v_mov_b32_e32 v69, v173
	v_lshl_add_u64 v[70:71], s[34:35], 0, v[66:67]
	v_lshl_add_u64 v[70:71], v[70:71], 0, v[68:69]
	v_lshl_add_u64 v[72:73], s[36:37], 0, v[66:67]
	v_lshl_add_u64 v[72:73], v[72:73], 0, v[68:69]
	v_ashrrev_i32_e32 v74, 3, v43
	v_lshlrev_b32_e32 v74, 6, v74
	v_ashrrev_i32_e32 v75, 31, v74
	v_lshlrev_b64 v[74:75], 1, v[74:75]
	v_lshl_add_u64 v[76:77], v[70:71], 0, v[74:75]
	global_load_dwordx4 v[100:103], v[76:77], off
	v_lshl_add_u64 v[76:77], v[72:73], 0, v[74:75]
	global_load_dwordx4 v[104:107], v[76:77], off
	v_add_u32_e32 v74, 0x100, v43
	v_ashrrev_i32_e32 v74, 3, v74
	v_lshlrev_b32_e32 v74, 6, v74
	v_ashrrev_i32_e32 v75, 31, v74
	v_lshlrev_b64 v[74:75], 1, v[74:75]
	v_lshl_add_u64 v[76:77], v[70:71], 0, v[74:75]
	global_load_dwordx4 v[108:111], v[76:77], off
	v_lshl_add_u64 v[76:77], v[72:73], 0, v[74:75]
	global_load_dwordx4 v[112:115], v[76:77], off
	v_mov_b64_e32 v[4:5], 0
	v_ashrrev_i32_e32 v9, 31, v8
	s_and_saveexec_b64 s[38:39], s[68:69]
	s_cbranch_execz .LBB0_1460
	v_readlane_b32 s40, v254, 41
	v_readlane_b32 s46, v254, 47
	v_readlane_b32 s47, v254, 48
	v_lshl_add_u64 v[4:5], s[30:31], 0, v[8:9]
	v_readlane_b32 s41, v254, 42
	v_mov_b64_e32 v[6:7], s[46:47]
	v_mad_u64_u32 v[6:7], s[10:11], v4, s97, v[6:7]
	v_mad_i32_i24 v7, v5, s97, v7
	v_lshl_add_u64 v[4:5], v[6:7], 0, v[172:173]
	v_readlane_b32 s42, v254, 43
	v_readlane_b32 s43, v254, 44
	v_readlane_b32 s44, v254, 45
	v_readlane_b32 s45, v254, 46
	v_readlane_b32 s48, v254, 49
	v_readlane_b32 s49, v254, 50
	v_readlane_b32 s50, v254, 51
	v_readlane_b32 s51, v254, 52
	v_readlane_b32 s52, v254, 53
	v_readlane_b32 s53, v254, 54
	v_readlane_b32 s54, v254, 55
	v_readlane_b32 s55, v254, 56

; DI void lru1_item(const Params& p, int l, int it, char* smem) {
;     ...
;     for (int j = 0; j < 19; ++j) {
;       const int tl = tq * 16 - 3 + j;
;       const int tt = t0 + tl;
;       float v = 0.f;
;       if (tl < Lc) {
;         if (tt >= 0) v = LX[(size_t)(row0 + tl) * 512 + ch];
;         else if (isS) v = buf[(3 + tt) * 512];
;       }
;       x[j] = v;
.LBB0_1465:
	s_andn2_saveexec_b64 s[40:41], s[40:41]
	s_cbranch_execz .LBB0_1467
	v_add_u32_e32 v22, v23, v1
	v_ashrrev_i32_e32 v23, 31, v22
	v_lshlrev_b64 v[22:23], 11, v[22:23]
	v_lshl_add_u64 v[22:23], v[6:7], 0, v[22:23]
	global_load_dword v22, v[22:23], off

; DI void lru1_item(const Params& p, int l, int it, char* smem) {
;     ...
;     for (int j = 0; j < 19; ++j) {
;       const int tl = tq * 16 - 3 + j;
;       const int tt = t0 + tl;
;       float v = 0.f;
;       if (tl < Lc) {
;         if (tt >= 0) v = LX[(size_t)(row0 + tl) * 512 + ch];
;         else if (isS) v = buf[(3 + tt) * 512];
;       }
;       x[j] = v;
.LBB0_1481:
	s_andn2_saveexec_b64 s[40:41], s[40:41]
	s_cbranch_execz .LBB0_1483
	v_add_u32_e32 v24, v25, v1
	v_ashrrev_i32_e32 v25, 31, v24
	v_lshlrev_b64 v[24:25], 11, v[24:25]
	v_lshl_add_u64 v[24:25], v[6:7], 0, v[24:25]
	global_load_dword v24, v[24:25], off

; DI void lru1_item(const Params& p, int l, int it, char* smem) {
;     ...
;     for (int j = 0; j < 19; ++j) {
;       const int tl = tq * 16 - 3 + j;
;       const int tt = t0 + tl;
;       float v = 0.f;
;       if (tl < Lc) {
;         if (tt >= 0) v = LX[(size_t)(row0 + tl) * 512 + ch];
;         else if (isS) v = buf[(3 + tt) * 512];
;       }
;       x[j] = v;
.LBB0_1497:
	s_andn2_saveexec_b64 s[44:45], s[44:45]
	s_cbranch_execz .LBB0_1499
	v_add_u32_e32 v26, v44, v1
	v_ashrrev_i32_e32 v27, 31, v26
	v_lshlrev_b64 v[26:27], 11, v[26:27]
	v_lshl_add_u64 v[26:27], v[6:7], 0, v[26:27]
	global_load_dword v26, v[26:27], off

; DI void lru1_item(const Params& p, int l, int it, char* smem) {
;     ...
;     for (int j = 0; j < 19; ++j) {
;       const int tl = tq * 16 - 3 + j;
;       const int tt = t0 + tl;
;       float v = 0.f;
;       if (tl < Lc) {
;         if (tt >= 0) v = LX[(size_t)(row0 + tl) * 512 + ch];
;         else if (isS) v = buf[(3 + tt) * 512];
;       }
;       x[j] = v;
.LBB0_1513:
	s_andn2_saveexec_b64 s[48:49], s[48:49]
	s_cbranch_execz .LBB0_1515
	v_add_u32_e32 v28, v46, v1
	v_ashrrev_i32_e32 v29, 31, v28
	v_lshlrev_b64 v[28:29], 11, v[28:29]
	v_lshl_add_u64 v[28:29], v[6:7], 0, v[28:29]
	global_load_dword v28, v[28:29], off

; DI void lru1_item(const Params& p, int l, int it, char* smem) {
;     ...
;     for (int j = 0; j < 19; ++j) {
;       const int tl = tq * 16 - 3 + j;
;       const int tt = t0 + tl;
;       float v = 0.f;
;       if (tl < Lc) {
;         if (tt >= 0) v = LX[(size_t)(row0 + tl) * 512 + ch];
;         else if (isS) v = buf[(3 + tt) * 512];
;       }
;       x[j] = v;
.LBB0_1529:
	s_andn2_saveexec_b64 s[52:53], s[52:53]
	s_cbranch_execz .LBB0_1531
	v_add_u32_e32 v30, v48, v1
	v_ashrrev_i32_e32 v31, 31, v30
	v_lshlrev_b64 v[30:31], 11, v[30:31]
	v_lshl_add_u64 v[30:31], v[6:7], 0, v[30:31]
	global_load_dword v30, v[30:31], off

; DI void lru1_item(const Params& p, int l, int it, char* smem) {
;     ...
;     for (int j = 0; j < 19; ++j) {
;       const int tl = tq * 16 - 3 + j;
;       const int tt = t0 + tl;
;       float v = 0.f;
;       if (tl < Lc) {
;         if (tt >= 0) v = LX[(size_t)(row0 + tl) * 512 + ch];
;         else if (isS) v = buf[(3 + tt) * 512];
;       }
;       x[j] = v;
.LBB0_1545:
	s_andn2_saveexec_b64 s[56:57], s[56:57]
	s_cbranch_execz .LBB0_1547
	v_add_u32_e32 v32, v50, v1
	v_ashrrev_i32_e32 v33, 31, v32
	v_lshlrev_b64 v[32:33], 11, v[32:33]
	v_lshl_add_u64 v[32:33], v[6:7], 0, v[32:33]
	global_load_dword v32, v[32:33], off

; DI void lru1_item(const Params& p, int l, int it, char* smem) {
;     ...
;     for (int j = 0; j < 19; ++j) {
;       const int tl = tq * 16 - 3 + j;
;       const int tt = t0 + tl;
;       float v = 0.f;
;       if (tl < Lc) {
;         if (tt >= 0) v = LX[(size_t)(row0 + tl) * 512 + ch];
;         else if (isS) v = buf[(3 + tt) * 512];
;       }
;       x[j] = v;
.LBB0_1561:
	s_andn2_saveexec_b64 s[60:61], s[60:61]
	s_cbranch_execz .LBB0_1563
	v_add_u32_e32 v34, v52, v1
	v_ashrrev_i32_e32 v35, 31, v34
	v_lshlrev_b64 v[34:35], 11, v[34:35]
	v_lshl_add_u64 v[34:35], v[6:7], 0, v[34:35]
	global_load_dword v34, v[34:35], off

; DI void lru1_item(const Params& p, int l, int it, char* smem) {
;     ...
;     for (int j = 0; j < 19; ++j) {
;       const int tl = tq * 16 - 3 + j;
;       const int tt = t0 + tl;
;       float v = 0.f;
;       if (tl < Lc) {
;         if (tt >= 0) v = LX[(size_t)(row0 + tl) * 512 + ch];
;         else if (isS) v = buf[(3 + tt) * 512];
;       }
;       x[j] = v;
.LBB0_1577:
	s_andn2_saveexec_b64 s[64:65], s[64:65]
	s_cbranch_execz .LBB0_1579
	v_add_u32_e32 v36, v54, v1
	v_ashrrev_i32_e32 v37, 31, v36
	v_lshlrev_b64 v[36:37], 11, v[36:37]
	v_lshl_add_u64 v[36:37], v[6:7], 0, v[36:37]
	global_load_dword v36, v[36:37], off

; DI void lru1_item(const Params& p, int l, int it, char* smem) {
;     ...
;     for (int j = 0; j < 19; ++j) {
;       const int tl = tq * 16 - 3 + j;
;       const int tt = t0 + tl;
;       float v = 0.f;
;       if (tl < Lc) {
;         if (tt >= 0) v = LX[(size_t)(row0 + tl) * 512 + ch];
;         else if (isS) v = buf[(3 + tt) * 512];
;       }
;       x[j] = v;
.LBB0_1593:
	s_andn2_saveexec_b64 s[64:65], s[64:65]
	s_cbranch_execz .LBB0_1595
	v_add_u32_e32 v38, v56, v1
	v_ashrrev_i32_e32 v39, 31, v38
	v_lshlrev_b64 v[38:39], 11, v[38:39]
	v_lshl_add_u64 v[38:39], v[6:7], 0, v[38:39]
	global_load_dword v38, v[38:39], off

; DI void lru1_item(const Params& p, int l, int it, char* smem) {
;     ...
; #pragma unroll
;     for (int k = 0; k < 16; ++k) {
;       const int t = tq * 16 + k;
;       const float xv = (t < Lc) ? cb + w0 * x[k] + w1 * x[k + 1] + w2 * x[k + 2] + w3 * x[k + 3] : 0.f;
;       xcs[t * LP + i] = f2bf(xv);
;     }
; #pragma unroll
;     for (int k = 0; k < 2; ++k) {
;       const int id = tid + k * 256, r = id >> 3, c8 = id & 7;
;       *(uint4*)(was + r * LP + c8 * 8) = *(const uint4*)(Wl + W_WA + nb * 4096 + r * 64 + c8 * 8);
;       *(uint4*)(wxs + r * LP + c8 * 8) = *(const uint4*)(Wl + W_WX + nb * 4096 + r * 64 + c8 * 8);
;     }
;     const int T = isS ? STT : PT;
;     if (t0 + Lc == T && tid < 192) {
;       const int k = tid >> 6;
;       const float v = LX[(size_t)(row0 + Lc - 3 + k) * 512 + ch];
;       if (isS) p.out[LC_S + (((size_t)l * SBT + b) * 3 + k) * 512 + ch] = v;
;       else p.out[LC_P + (((size_t)l * PB + b) * 3 + k) * 512 + ch] = v;
;     }
.LBB0_1612:
	s_or_b64 exec, exec, s[74:75]
	s_waitcnt vmcnt(0)
	v_fma_f32 v4, v11, v22, v17
	v_fmac_f32_e32 v4, v15, v21
	v_lshrrev_b32_e32 v59, 8, v19
	s_mov_b32 s10, 0x12000
	v_fmac_f32_e32 v4, v16, v24
	v_mad_i32_i24 v60, v59, s10, 16
	v_fmac_f32_e32 v4, v18, v23
	s_movk_i32 s10, 0x900
	v_cvt_pk_bf16_f32 v4, v4, s0
	v_mul_lo_u32 v5, v12, s10
	v_lshlrev_b32_e32 v6, 1, v20
	v_cndmask_b32_e64 v4, 0, v4, s[38:39]
	v_add3_u32 v5, v60, v5, v6
	ds_write_b16 v5, v4
	v_fma_f32 v4, v11, v21, v17
	v_fmac_f32_e32 v4, v15, v24
	v_fmac_f32_e32 v4, v16, v23
	v_fmac_f32_e32 v4, v18, v26
	v_cvt_pk_bf16_f32 v4, v4, s0
	v_mul_lo_u32 v5, v44, s70
	v_cndmask_b32_e64 v4, 0, v4, s[40:41]
	v_add3_u32 v5, v60, v5, v6
	ds_write_b16 v5, v4
	v_fma_f32 v4, v11, v24, v17
	v_fmac_f32_e32 v4, v15, v23
	v_fmac_f32_e32 v4, v16, v26
	v_fmac_f32_e32 v4, v18, v25
	v_cvt_pk_bf16_f32 v4, v4, s0
	v_cndmask_b32_e64 v4, 0, v4, s[42:43]
	ds_write_b16 v5, v4 offset:144
	v_fma_f32 v4, v11, v23, v17
	v_fmac_f32_e32 v4, v15, v26
	v_fmac_f32_e32 v4, v16, v25
	v_fmac_f32_e32 v4, v18, v28
	v_cvt_pk_bf16_f32 v4, v4, s0
	v_cndmask_b32_e64 v4, 0, v4, s[44:45]
	ds_write_b16 v5, v4 offset:288
	v_fma_f32 v4, v11, v26, v17
	v_fmac_f32_e32 v4, v15, v25
	v_fmac_f32_e32 v4, v16, v28
	v_fmac_f32_e32 v4, v18, v27
	v_cvt_pk_bf16_f32 v4, v4, s0
	v_cndmask_b32_e64 v4, 0, v4, s[46:47]
	ds_write_b16 v5, v4 offset:432
	v_fma_f32 v4, v11, v25, v17
	v_fmac_f32_e32 v4, v15, v28
	v_fmac_f32_e32 v4, v16, v27
	v_fmac_f32_e32 v4, v18, v30
	v_cvt_pk_bf16_f32 v4, v4, s0
	v_cndmask_b32_e64 v4, 0, v4, s[48:49]
	ds_write_b16 v5, v4 offset:576
	v_fma_f32 v4, v11, v28, v17
	v_fmac_f32_e32 v4, v15, v27
	v_fmac_f32_e32 v4, v16, v30
	v_fmac_f32_e32 v4, v18, v29
	v_cvt_pk_bf16_f32 v4, v4, s0
	v_cndmask_b32_e64 v4, 0, v4, s[50:51]
	ds_write_b16 v5, v4 offset:720
	v_fma_f32 v4, v11, v27, v17
	v_fmac_f32_e32 v4, v15, v30
	v_fmac_f32_e32 v4, v16, v29
	v_fmac_f32_e32 v4, v18, v32
	v_cvt_pk_bf16_f32 v4, v4, s0
	v_cndmask_b32_e64 v4, 0, v4, s[52:53]
	ds_write_b16 v5, v4 offset:864
	v_fma_f32 v4, v11, v30, v17
	v_fmac_f32_e32 v4, v15, v29
	v_fmac_f32_e32 v4, v16, v32
	v_fmac_f32_e32 v4, v18, v31
	v_cvt_pk_bf16_f32 v4, v4, s0
	v_cndmask_b32_e64 v4, 0, v4, s[54:55]
	ds_write_b16 v5, v4 offset:1008
	v_fma_f32 v4, v11, v29, v17
	v_fmac_f32_e32 v4, v15, v32
	v_fmac_f32_e32 v4, v16, v31
	v_fmac_f32_e32 v4, v18, v34
	v_cvt_pk_bf16_f32 v4, v4, s0
	v_cndmask_b32_e64 v4, 0, v4, s[56:57]
	ds_write_b16 v5, v4 offset:1152
	v_fma_f32 v4, v11, v32, v17
	v_fmac_f32_e32 v4, v15, v31
	v_fmac_f32_e32 v4, v16, v34
	v_fmac_f32_e32 v4, v18, v33
	v_cvt_pk_bf16_f32 v4, v4, s0
	v_cndmask_b32_e64 v4, 0, v4, s[58:59]
	ds_write_b16 v5, v4 offset:1296
	v_fma_f32 v4, v11, v31, v17
	v_fmac_f32_e32 v4, v15, v34
	v_fmac_f32_e32 v4, v16, v33
	v_fmac_f32_e32 v4, v18, v36
	v_cvt_pk_bf16_f32 v4, v4, s0
	v_cndmask_b32_e64 v4, 0, v4, s[60:61]
	ds_write_b16 v5, v4 offset:1440
	v_fma_f32 v4, v11, v34, v17
	v_fmac_f32_e32 v4, v15, v33
	v_fmac_f32_e32 v4, v16, v36
	v_fmac_f32_e32 v4, v18, v35
	v_cvt_pk_bf16_f32 v4, v4, s0
	v_cndmask_b32_e64 v4, 0, v4, s[62:63]
	ds_write_b16 v5, v4 offset:1584
	v_fma_f32 v4, v11, v33, v17
	v_fmac_f32_e32 v4, v15, v36
	v_fmac_f32_e32 v4, v16, v35
	v_fmac_f32_e32 v4, v18, v38
	v_cvt_pk_bf16_f32 v4, v4, s0
	v_cndmask_b32_e32 v4, 0, v4, vcc
	ds_write_b16 v5, v4 offset:1728
	v_fma_f32 v4, v11, v36, v17
	v_fmac_f32_e32 v4, v15, v35
	v_fmac_f32_e32 v4, v16, v38
	v_fmac_f32_e32 v17, v11, v35
	v_fmac_f32_e32 v4, v18, v37
	v_fmac_f32_e32 v17, v15, v38
	v_cvt_pk_bf16_f32 v4, v4, s0
	v_fmac_f32_e32 v17, v16, v37
	v_cndmask_b32_e64 v4, 0, v4, s[64:65]
	v_fmac_f32_e32 v17, v18, v39
	ds_write_b16 v5, v4 offset:1872
	v_cvt_pk_bf16_f32 v4, v17, s0
	v_cndmask_b32_e64 v4, 0, v4, s[66:67]
	ds_write_b16 v5, v4 offset:2016
	v_lshlrev_b32_e32 v4, 13, v10
	v_mov_b32_e32 v5, v173
	v_lshlrev_b32_e32 v10, 4, v43
	v_lshl_add_u64 v[6:7], s[34:35], 0, v[4:5]
	v_and_b32_e32 v10, 0x70, v10
	v_mov_b32_e32 v11, v173
	v_lshl_add_u64 v[16:17], v[6:7], 0, v[10:11]
	v_lshl_add_u64 v[4:5], s[36:37], 0, v[4:5]
	v_ashrrev_i32_e32 v6, 3, v43
	v_lshl_add_u64 v[22:23], v[4:5], 0, v[10:11]
	v_lshlrev_b32_e32 v4, 6, v6
	v_ashrrev_i32_e32 v5, 31, v4
	v_add_u32_e32 v18, v60, v10
	v_lshlrev_b64 v[10:11], 1, v[4:5]
	v_lshl_add_u64 v[4:5], v[16:17], 0, v[10:11]
	v_mad_u64_u32 v[24:25], s[10:11], v6, s70, v[18:19]
	ds_write_b128 v24, v[100:103] offset:9216
	v_lshl_add_u64 v[4:5], v[22:23], 0, v[10:11]
	ds_write_b128 v24, v[104:107] offset:18432
	v_add_u32_e32 v4, 0x100, v43
	v_ashrrev_i32_e32 v6, 3, v4
	v_lshlrev_b32_e32 v4, 6, v6
	v_ashrrev_i32_e32 v5, 31, v4
	v_lshlrev_b64 v[24:25], 1, v[4:5]
	v_lshl_add_u64 v[4:5], v[16:17], 0, v[24:25]
	v_mad_u64_u32 v[10:11], s[10:11], v6, s70, v[18:19]
	s_movk_i32 s10, 0xc0
	v_cmp_gt_i32_e64 s[74:75], s10, v43
	ds_write_b128 v10, v[108:111] offset:9216
	v_lshl_add_u64 v[4:5], v[22:23], 0, v[24:25]
	ds_write_b128 v10, v[112:115] offset:18432
	v_cndmask_b32_e64 v4, v187, 32, s[68:69]
	v_add_u32_e32 v5, v40, v13
	v_cmp_eq_u32_e64 s[72:73], v5, v4
	s_and_b64 s[10:11], s[72:73], s[74:75]
	s_and_saveexec_b64 s[72:73], s[10:11]
	s_cbranch_execz .LBB0_1614
	v_add_u32_e32 v4, v1, v40
	v_add3_u32 v4, v4, v12, -3
	v_ashrrev_i32_e32 v5, 31, v4
	v_readlane_b32 s10, v252, 33
	v_lshlrev_b64 v[4:5], 11, v[4:5]
	v_readlane_b32 s11, v252, 34
	v_ashrrev_i32_e32 v13, 31, v12
	v_mov_b32_e32 v6, 0x28400000
	v_lshl_add_u64 v[4:5], s[10:11], 0, v[4:5]
	v_lshl_add_u64 v[4:5], v[4:5], 0, v[172:173]
	global_load_dword v10, v[4:5], off
	v_readlane_b32 s10, v254, 39
	v_cndmask_b32_e64 v4, 2, 4, s[68:69]
	v_readlane_b32 s11, v254, 40
	v_mov_b32_e32 v7, 0x29478000
	v_cndmask_b32_e64 v6, v6, v7, s[68:69]
	v_lshlrev_b64 v[4:5], v4, s[10:11]
	v_lshl_add_u64 v[4:5], v[4:5], 0, v[8:9]
	v_mad_u64_u32 v[8:9], s[10:11], v4, 3, v[12:13]
	v_mad_i32_i24 v9, v5, 3, v9
	v_lshlrev_b64 v[4:5], 11, v[8:9]
	v_mov_b32_e32 v7, v173
	v_lshl_add_u64 v[4:5], s[92:93], 0, v[4:5]
	v_lshl_add_u64 v[4:5], v[4:5], 0, v[6:7]
	v_lshl_add_u64 v[4:5], v[4:5], 0, v[172:173]
	s_waitcnt vmcnt(0)
	global_store_dword v[4:5], v10, off

; DI int TID() { int t = threadIdx.x & 255; asm volatile("" : "+v"(t)); return t; }
; #define VB() (2 * B + (TID512() >> 8))
; #define HS() (smem + (TID512() >> 8) * HALF_LDS)
; DI void lru3_item(const Params& p, int it) {
;   const u16* HL = (const u16*)(p.ws + O_HL);
;   const u16* PPp = (const u16*)(p.ws + O_PP);
;   const u16* LG = (const u16*)(p.ws + O_LG);
;   const float* HS = (const float*)(p.ws + O_HS);
;   u16* OL = (u16*)(p.ws + O_OL);
; #pragma unroll
;   for (int i = 0; i < 4; ++i) {
;     const int id = TID() + i * 256;
;     const int row = it * 8 + (id >> 7), c4 = (id & 127) * 4;
;     const int ci = row < MP ? (row >> 6) : MP / 64 + ((row - MP) >> 5);
;     const size_t o = (size_t)row * 512 + c4;
; __global__ void __launch_bounds__(512, 2) mega(Params p) {
;     ...
;     if (ONLY < 0 || ONLY == 5) { for (int it = VB(); it < NGI; it += vG) gla3_item(p, l, it, HS()); for (int it = VB(); it < L3_ITEMS; it += vG) lru3_item(p, it); }
.LBB0_1906:
	s_or_b64 exec, exec, s[40:41]
	v_mov_b32_e32 v0, v184
	v_readlane_b32 s4, v251, 5
	v_ashrrev_i32_e32 v0, 8, v0
	v_readlane_b32 s5, v251, 6
	v_add_u32_e32 v2, s4, v0
	v_add_u32_e32 v2, 0x1c0, v2
	v_and_b32_e32 v2, 0x1ff, v2
	s_movk_i32 s4, 0x1040
	v_cmp_gt_i32_e32 vcc, s4, v2
	s_and_saveexec_b64 s[4:5], vcc
	v_readlane_b32 s10, v252, 31
	v_readlane_b32 s12, v253, 1
	v_readlane_b32 s24, v253, 3
	v_readlane_b32 s26, v253, 9
	v_readlane_b32 s28, v253, 13
	v_readlane_b32 s11, v252, 32
	v_readlane_b32 s13, v253, 2
	v_readlane_b32 s25, v253, 4
	v_readlane_b32 s27, v253, 10
	v_readlane_b32 s29, v253, 14
	v_readlane_b32 s9, v253, 24
	s_mov_b32 s20, 0x8000
	s_cbranch_execz .LBB0_1909
	v_readlane_b32 s6, v253, 15
	s_nop 1
	v_lshlrev_b32_e32 v4, 3, v2
	s_mov_b64 s[6:7], 0

; DI int TID512() { int t = threadIdx.x; asm volatile("" : "+v"(t)); return t; }
; template <bool ADD>
; DI void imgf_store(float* dst, const float* rsrc, int ld, const char* smem) {
;   const int tid = TID512();
;   const unsigned o0 = (unsigned)((tid >> 6) * ld + (tid & 63) * 4);
;   const char* src = smem + (tid >> 6) * (IMGF_LD * 4) + (tid & 63) * 16;
; #pragma unroll
;   for (int q = 0; q < 16; ++q) {
;     if ((q & 3) == 0) asm volatile("" ::: "memory");
;     float4 v = *(const float4*)(src + q * 8 * (IMGF_LD * 4));
;     float4* d = (float4*)(dst + (o0 + (unsigned)(q * 8 * ld)));
;     if (ADD) { const f32x4 x = __builtin_nontemporal_load((const f32x4*)(rsrc + (o0 + (unsigned)(q * 8 * ld)))); v.x += x[0]; v.y += x[1]; v.z += x[2]; v.w += x[3]; }
;     if (ADD) *d = v;
;     else __builtin_nontemporal_store(f32x4{v.x, v.y, v.z, v.w}, (f32x4*)d);
;   }
.LBB0_2109:
	s_or_b64 exec, exec, s[8:9]
	s_lshl_b32 s20, s20, 17
	v_mov_b32_e32 v0, v184
	s_xor_b64 s[8:9], s[12:13], -1
	s_waitcnt lgkmcnt(0)
	s_barrier
	s_lshl_b64 s[12:13], s[20:21], 2
	s_add_u32 s26, s5, s12
	v_ashrrev_i32_e32 v1, 6, v0
	v_and_b32_e32 v0, 63, v0
	s_addc_u32 s27, s7, s13
	v_lshlrev_b32_e32 v2, 2, v0
	s_add_u32 s12, s28, s12
	v_lshl_or_b32 v172, v1, 10, v2
	s_addc_u32 s13, s29, s13
	v_lshlrev_b64 v[132:133], 2, v[172:173]
	v_lshl_add_u64 v[140:141], s[26:27], 0, v[132:133]
	v_mul_lo_u32 v1, v1, s71
	v_lshlrev_b32_e32 v0, 4, v0
	v_add3_u32 v0, 16, v1, v0
	v_add_u32_e32 v1, 0x10400, v0
	s_mov_b64 s[24:25], 0x8000
	ds_read_b128 v[230:233], v0
	ds_read_b128 v[234:237], v0 offset:8320
	ds_read_b128 v[238:241], v0 offset:16640
	ds_read_b128 v[242:245], v0 offset:24960
	s_waitcnt vmcnt(15) lgkmcnt(3)
	v_pk_add_f32 v[144:145], v[230:231], v[144:145]
	v_pk_add_f32 v[146:147], v[232:233], v[146:147]
	global_store_dwordx4 v[140:141], v[144:147], off
	v_lshl_add_u64 v[140:141], v[140:141], 0, s[24:25]
	ds_read_b128 v[230:233], v0 offset:33280
	s_waitcnt vmcnt(15) lgkmcnt(3)
	v_pk_add_f32 v[148:149], v[234:235], v[148:149]
	v_pk_add_f32 v[150:151], v[236:237], v[150:151]
	global_store_dwordx4 v[140:141], v[148:151], off
	v_lshl_add_u64 v[140:141], v[140:141], 0, s[24:25]
	ds_read_b128 v[234:237], v0 offset:41600
	s_waitcnt vmcnt(15) lgkmcnt(3)
	v_pk_add_f32 v[152:153], v[238:239], v[152:153]
	v_pk_add_f32 v[154:155], v[240:241], v[154:155]
	global_store_dwordx4 v[140:141], v[152:155], off
	v_lshl_add_u64 v[140:141], v[140:141], 0, s[24:25]
	ds_read_b128 v[238:241], v0 offset:49920
	s_waitcnt vmcnt(15) lgkmcnt(3)
	v_pk_add_f32 v[156:157], v[242:243], v[156:157]
	v_pk_add_f32 v[158:159], v[244:245], v[158:159]
	global_store_dwordx4 v[140:141], v[156:159], off
	v_lshl_add_u64 v[140:141], v[140:141], 0, s[24:25]
	ds_read_b128 v[242:245], v0 offset:58240
	s_waitcnt vmcnt(15) lgkmcnt(3)
	v_pk_add_f32 v[160:161], v[230:231], v[160:161]
	v_pk_add_f32 v[162:163], v[232:233], v[162:163]
	global_store_dwordx4 v[140:141], v[160:163], off
	v_lshl_add_u64 v[140:141], v[140:141], 0, s[24:25]
	ds_read_b128 v[230:233], v1
	s_waitcnt vmcnt(15) lgkmcnt(3)
	v_pk_add_f32 v[164:165], v[234:235], v[164:165]
	v_pk_add_f32 v[166:167], v[236:237], v[166:167]
	global_store_dwordx4 v[140:141], v[164:167], off
	v_lshl_add_u64 v[140:141], v[140:141], 0, s[24:25]
	ds_read_b128 v[234:237], v1 offset:8320
	s_waitcnt vmcnt(15) lgkmcnt(3)
	v_pk_add_f32 v[168:169], v[238:239], v[168:169]
	v_pk_add_f32 v[170:171], v[240:241], v[170:171]
	global_store_dwordx4 v[140:141], v[168:171], off
	v_lshl_add_u64 v[140:141], v[140:141], 0, s[24:25]
	ds_read_b128 v[238:241], v1 offset:16640
	s_waitcnt vmcnt(15) lgkmcnt(3)
	v_pk_add_f32 v[176:177], v[242:243], v[176:177]
	v_pk_add_f32 v[178:179], v[244:245], v[178:179]
	global_store_dwordx4 v[140:141], v[176:179], off
	v_lshl_add_u64 v[140:141], v[140:141], 0, s[24:25]
	ds_read_b128 v[242:245], v1 offset:24960
	s_waitcnt vmcnt(15) lgkmcnt(3)
	v_pk_add_f32 v[180:181], v[230:231], v[180:181]
	v_pk_add_f32 v[182:183], v[232:233], v[182:183]
	global_store_dwordx4 v[140:141], v[180:183], off
	v_lshl_add_u64 v[140:141], v[140:141], 0, s[24:25]
	ds_read_b128 v[230:233], v1 offset:33280
	s_waitcnt vmcnt(15) lgkmcnt(3)
	v_pk_add_f32 v[198:199], v[234:235], v[198:199]
	v_pk_add_f32 v[200:201], v[236:237], v[200:201]
	global_store_dwordx4 v[140:141], v[198:201], off
	v_lshl_add_u64 v[140:141], v[140:141], 0, s[24:25]
	ds_read_b128 v[234:237], v1 offset:41600
	s_waitcnt vmcnt(15) lgkmcnt(3)
	v_pk_add_f32 v[202:203], v[238:239], v[202:203]
	v_pk_add_f32 v[204:205], v[240:241], v[204:205]
	global_store_dwordx4 v[140:141], v[202:205], off
	v_lshl_add_u64 v[140:141], v[140:141], 0, s[24:25]
	ds_read_b128 v[238:241], v1 offset:49920
	s_waitcnt vmcnt(15) lgkmcnt(3)
	v_pk_add_f32 v[206:207], v[242:243], v[206:207]
	v_pk_add_f32 v[208:209], v[244:245], v[208:209]
	global_store_dwordx4 v[140:141], v[206:209], off
	v_lshl_add_u64 v[140:141], v[140:141], 0, s[24:25]
	ds_read_b128 v[242:245], v1 offset:58240
	s_waitcnt vmcnt(15) lgkmcnt(3)
	v_pk_add_f32 v[214:215], v[230:231], v[214:215]
	v_pk_add_f32 v[216:217], v[232:233], v[216:217]
	global_store_dwordx4 v[140:141], v[214:217], off
	v_lshl_add_u64 v[140:141], v[140:141], 0, s[24:25]
	s_waitcnt vmcnt(15) lgkmcnt(2)
	v_pk_add_f32 v[218:219], v[234:235], v[218:219]
	v_pk_add_f32 v[220:221], v[236:237], v[220:221]
	global_store_dwordx4 v[140:141], v[218:221], off
	v_lshl_add_u64 v[140:141], v[140:141], 0, s[24:25]
	s_waitcnt vmcnt(15) lgkmcnt(1)
	v_pk_add_f32 v[222:223], v[238:239], v[222:223]
	v_pk_add_f32 v[224:225], v[240:241], v[224:225]
	global_store_dwordx4 v[140:141], v[222:225], off
	v_lshl_add_u64 v[140:141], v[140:141], 0, s[24:25]
	s_waitcnt vmcnt(15) lgkmcnt(0)
	v_pk_add_f32 v[226:227], v[242:243], v[226:227]
	v_pk_add_f32 v[228:229], v[244:245], v[228:229]
	global_store_dwordx4 v[140:141], v[226:229], off
	s_mov_b32 s20, 1
	s_and_b64 vcc, exec, s[8:9]
	s_mov_b64 s[12:13], 0
	s_cbranch_vccnz .LBB0_2112
; DI void img_barrier() { asm volatile("s_waitcnt lgkmcnt(0)" ::: "memory"); __builtin_amdgcn_s_barrier(); }
; template <bool ADD>
; DI void imgf_store(float* dst, const float* rsrc, int ld, const char* smem) {
;     ...
;     float4 v = *(const float4*)(src + q * 8 * (IMGF_LD * 4));
;     float4* d = (float4*)(dst + (o0 + (unsigned)(q * 8 * ld)));
;     if (ADD) { const f32x4 x = __builtin_nontemporal_load((const f32x4*)(rsrc + (o0 + (unsigned)(q * 8 * ld)))); v.x += x[0]; v.y += x[1]; v.z += x[2]; v.w += x[3]; }
; template <bool ADD, bool ROPE>
; DI void tile_out_f32(const f32x4 (&acc)[8][4], float* dst, int ld, char* smem, int prow0, const float* cosT, const float* rsrc = nullptr) {
; #pragma unroll 1
;   for (int h = 0; h < 2; ++h) {
;     img_barrier();
;     imgf_put<ROPE>(acc, h, smem, prow0, cosT);
;     img_barrier();
;     imgf_store<ADD>(dst + (size_t)h * 128 * ld, ADD ? rsrc + (size_t)h * 128 * ld : nullptr, ld, smem);
.LBB0_2110:
	s_waitcnt lgkmcnt(0)
	v_mov_b32_e32 v0, v184
	s_barrier
	s_lshl_b32 s34, s20, 19
	s_add_u32 s48, s28, s34
	s_addc_u32 s49, s29, 0
	v_ashrrev_i32_e32 v134, 6, v184
	v_and_b32_e32 v135, 63, v184
	v_lshlrev_b32_e32 v135, 2, v135
	v_lshl_or_b32 v172, v134, 10, v135
	v_lshl_add_u64 v[132:133], v[172:173], 2, s[48:49]
	s_mov_b64 s[24:25], 0x8000
	global_load_dwordx4 v[144:147], v[132:133], off nt
	v_lshl_add_u64 v[132:133], v[132:133], 0, s[24:25]
	global_load_dwordx4 v[148:151], v[132:133], off nt
	v_lshl_add_u64 v[132:133], v[132:133], 0, s[24:25]
	global_load_dwordx4 v[152:155], v[132:133], off nt
	v_lshl_add_u64 v[132:133], v[132:133], 0, s[24:25]
	global_load_dwordx4 v[156:159], v[132:133], off nt
	v_lshl_add_u64 v[132:133], v[132:133], 0, s[24:25]
	global_load_dwordx4 v[160:163], v[132:133], off nt
	v_lshl_add_u64 v[132:133], v[132:133], 0, s[24:25]
	global_load_dwordx4 v[164:167], v[132:133], off nt
	v_lshl_add_u64 v[132:133], v[132:133], 0, s[24:25]
	global_load_dwordx4 v[168:171], v[132:133], off nt
	v_lshl_add_u64 v[132:133], v[132:133], 0, s[24:25]
	global_load_dwordx4 v[176:179], v[132:133], off nt
	v_lshl_add_u64 v[132:133], v[132:133], 0, s[24:25]
	global_load_dwordx4 v[180:183], v[132:133], off nt
	v_lshl_add_u64 v[132:133], v[132:133], 0, s[24:25]
	global_load_dwordx4 v[198:201], v[132:133], off nt
	v_lshl_add_u64 v[132:133], v[132:133], 0, s[24:25]
	global_load_dwordx4 v[202:205], v[132:133], off nt
	v_lshl_add_u64 v[132:133], v[132:133], 0, s[24:25]
	global_load_dwordx4 v[206:209], v[132:133], off nt
	v_lshl_add_u64 v[132:133], v[132:133], 0, s[24:25]
	global_load_dwordx4 v[214:217], v[132:133], off nt
	v_lshl_add_u64 v[132:133], v[132:133], 0, s[24:25]
	global_load_dwordx4 v[218:221], v[132:133], off nt
	v_lshl_add_u64 v[132:133], v[132:133], 0, s[24:25]
	global_load_dwordx4 v[222:225], v[132:133], off nt
	v_lshl_add_u64 v[132:133], v[132:133], 0, s[24:25]
	global_load_dwordx4 v[226:229], v[132:133], off nt
	s_nop 0
	v_ashrrev_i32_e32 v1, 8, v0
	v_cmp_eq_u32_e32 vcc, s20, v1
	s_and_saveexec_b64 s[8:9], vcc
	s_cbranch_execz .LBB0_2109
; template <bool ROPE>
; DI void imgf_put(const f32x4 (&acc)[8][4], int h, char* smem, int prow0, const float* cosT) {
;   EPI_IDS;
;   if (wr == h) {
;     float* f = (float*)smem + (fq * 4) * IMGF_LD + wc * 64 + fr;
; #pragma unroll
;     for (int m = 0; m < 8; ++m) {
;       float cs4[4] = {0.f, 0.f, 0.f, 0.f}, sn4[4] = {0.f, 0.f, 0.f, 0.f};
;       if (ROPE) {
; #pragma unroll
;         for (int j = 0; j < 4; ++j) { const int pos = prow0 + wr * 128 + m * 16 + fq * 4 + j; cs4[j] = cosT[pos * 8 + (fr & 7)]; sn4[j] = cosT[8192 * 8 + pos * 8 + (fr & 7)]; }
;       }
; #pragma unroll
;       for (int n = 0; n < 4; ++n)
; #pragma unroll
;         for (int j = 0; j < 4; ++j) f[(m * 16 + j) * IMGF_LD + n * 16] = epi_val<ROPE>(acc, m, n, j, cs4, sn4, fr);
;     }
;   }
; }
	v_and_b32_e32 v1, 15, v0
	v_and_b32_e32 v2, 0xc0, v0
	v_lshrrev_b32_e32 v0, 2, v0
	v_and_b32_e32 v0, 12, v0
	v_mad_u32_u24 v0, v0, s71, 16
	v_lshlrev_b32_e32 v2, 2, v2
	v_lshlrev_b32_e32 v1, 2, v1
	v_add3_u32 v0, v0, v2, v1
	v_add_u32_e32 v1, 0x400, v0
	v_add_u32_e32 v2, 0x800, v0
	v_add_u32_e32 v132, 0xc00, v0
	ds_write2_b32 v0, v128, v124 offset1:16
	ds_write2_b32 v1, v129, v125 offset0:4 offset1:20
	ds_write2_b32 v2, v130, v126 offset0:8 offset1:24
	ds_write2_b32 v132, v131, v127 offset0:12 offset1:28
	ds_write2_b32 v0, v120, v116 offset0:32 offset1:48
	ds_write2_b32 v1, v121, v117 offset0:36 offset1:52
	ds_write2_b32 v2, v122, v118 offset0:40 offset1:56
	ds_write2_b32 v132, v123, v119 offset0:44 offset1:60
	v_add_u32_e32 v1, 0x4000, v0
	v_add_u32_e32 v2, 0x4400, v0
	v_add_u32_e32 v132, 0x4800, v0
	v_add_u32_e32 v133, 0x4c00, v0
	ds_write2_b32 v1, v112, v108 offset0:64 offset1:80
	ds_write2_b32 v2, v113, v109 offset0:68 offset1:84
	ds_write2_b32 v132, v114, v110 offset0:72 offset1:88
	ds_write2_b32 v133, v115, v111 offset0:76 offset1:92
	ds_write2_b32 v1, v104, v100 offset0:96 offset1:112
	ds_write2_b32 v2, v105, v101 offset0:100 offset1:116
	ds_write2_b32 v132, v106, v102 offset0:104 offset1:120
	ds_write2_b32 v133, v107, v103 offset0:108 offset1:124
	v_add_u32_e32 v1, 0x8000, v0
	v_add_u32_e32 v2, 0x8400, v0
	v_add_u32_e32 v132, 0x8800, v0
	v_add_u32_e32 v133, 0x8c00, v0
	ds_write2_b32 v1, v96, v92 offset0:128 offset1:144
	ds_write2_b32 v2, v97, v93 offset0:132 offset1:148
	ds_write2_b32 v132, v98, v94 offset0:136 offset1:152
	ds_write2_b32 v133, v99, v95 offset0:140 offset1:156
	ds_write2_b32 v1, v88, v84 offset0:160 offset1:176
	ds_write2_b32 v2, v89, v85 offset0:164 offset1:180
	ds_write2_b32 v132, v90, v86 offset0:168 offset1:184
	ds_write2_b32 v133, v91, v87 offset0:172 offset1:188
	v_add_u32_e32 v1, 0xc000, v0
	v_add_u32_e32 v2, 0xc400, v0
	v_add_u32_e32 v132, 0xc800, v0
	v_add_u32_e32 v133, 0xcc00, v0
	ds_write2_b32 v1, v80, v76 offset0:192 offset1:208
	ds_write2_b32 v2, v81, v77 offset0:196 offset1:212
	ds_write2_b32 v132, v82, v78 offset0:200 offset1:216
	ds_write2_b32 v133, v83, v79 offset0:204 offset1:220
	ds_write2_b32 v1, v72, v68 offset0:224 offset1:240
	ds_write2_b32 v2, v73, v69 offset0:228 offset1:244
	ds_write2_b32 v132, v74, v70 offset0:232 offset1:248
	ds_write2_b32 v133, v75, v71 offset0:236 offset1:252
	v_add_u32_e32 v1, 0x10400, v0
	ds_write_b32 v1, v64
	v_add_u32_e32 v1, 0x10810, v0
	ds_write_b32 v1, v65
	v_add_u32_e32 v1, 0x10c20, v0
	ds_write_b32 v1, v66
	v_add_u32_e32 v1, 0x11030, v0
	ds_write_b32 v1, v67
	v_add_u32_e32 v1, 0x10440, v0
	ds_write_b32 v1, v60
	v_add_u32_e32 v1, 0x10850, v0
	ds_write_b32 v1, v61
	v_add_u32_e32 v1, 0x10c60, v0
	ds_write_b32 v1, v62
	v_add_u32_e32 v1, 0x11070, v0
	ds_write_b32 v1, v63
	v_add_u32_e32 v1, 0x10480, v0
	ds_write_b32 v1, v56
	v_add_u32_e32 v1, 0x10890, v0
	ds_write_b32 v1, v57
	v_add_u32_e32 v1, 0x10ca0, v0
	ds_write_b32 v1, v58
	v_add_u32_e32 v1, 0x110b0, v0
	ds_write_b32 v1, v59
	v_add_u32_e32 v1, 0x104c0, v0
	ds_write_b32 v1, v52
	v_add_u32_e32 v1, 0x108d0, v0
	ds_write_b32 v1, v53
	v_add_u32_e32 v1, 0x10ce0, v0
	ds_write_b32 v1, v54
	v_add_u32_e32 v1, 0x110f0, v0
	ds_write_b32 v1, v55
	v_add_u32_e32 v1, 0x14500, v0
	ds_write_b32 v1, v48
	v_add_u32_e32 v1, 0x14910, v0
	ds_write_b32 v1, v49
	v_add_u32_e32 v1, 0x14d20, v0
	ds_write_b32 v1, v50
	v_add_u32_e32 v1, 0x15130, v0
	ds_write_b32 v1, v51
	v_add_u32_e32 v1, 0x14540, v0
	ds_write_b32 v1, v44
	v_add_u32_e32 v1, 0x14950, v0
	ds_write_b32 v1, v45
	v_add_u32_e32 v1, 0x14d60, v0
	ds_write_b32 v1, v46
	v_add_u32_e32 v1, 0x15170, v0
	ds_write_b32 v1, v47
	v_add_u32_e32 v1, 0x14580, v0
	ds_write_b32 v1, v40
	v_add_u32_e32 v1, 0x14990, v0
	ds_write_b32 v1, v41
	v_add_u32_e32 v1, 0x14da0, v0
	ds_write_b32 v1, v42
	v_add_u32_e32 v1, 0x151b0, v0
	ds_write_b32 v1, v43
	v_add_u32_e32 v1, 0x145c0, v0
	ds_write_b32 v1, v36
	v_add_u32_e32 v1, 0x149d0, v0
	ds_write_b32 v1, v37
	v_add_u32_e32 v1, 0x14de0, v0
	ds_write_b32 v1, v38
	v_add_u32_e32 v1, 0x151f0, v0
	ds_write_b32 v1, v39
	v_add_u32_e32 v1, 0x18600, v0
	ds_write_b32 v1, v32
	v_add_u32_e32 v1, 0x18a10, v0
	ds_write_b32 v1, v33
	v_add_u32_e32 v1, 0x18e20, v0
	ds_write_b32 v1, v34
	v_add_u32_e32 v1, 0x19230, v0
	ds_write_b32 v1, v35
	v_add_u32_e32 v1, 0x18640, v0
	ds_write_b32 v1, v28
	v_add_u32_e32 v1, 0x18a50, v0
	ds_write_b32 v1, v29
	v_add_u32_e32 v1, 0x18e60, v0
	ds_write_b32 v1, v30
	v_add_u32_e32 v1, 0x19270, v0
	ds_write_b32 v1, v31
	v_add_u32_e32 v1, 0x18680, v0
	ds_write_b32 v1, v24
	v_add_u32_e32 v1, 0x18a90, v0
	ds_write_b32 v1, v25
	v_add_u32_e32 v1, 0x18ea0, v0
	ds_write_b32 v1, v26
	v_add_u32_e32 v1, 0x192b0, v0
	ds_write_b32 v1, v27
	v_add_u32_e32 v1, 0x186c0, v0
	ds_write_b32 v1, v20
	v_add_u32_e32 v1, 0x18ad0, v0
	ds_write_b32 v1, v21
	v_add_u32_e32 v1, 0x18ee0, v0
	ds_write_b32 v1, v22
	v_add_u32_e32 v1, 0x192f0, v0
	ds_write_b32 v1, v23
	v_add_u32_e32 v1, 0x1c700, v0
	ds_write_b32 v1, v16
	v_add_u32_e32 v1, 0x1cb10, v0
	ds_write_b32 v1, v17
	v_add_u32_e32 v1, 0x1cf20, v0
	ds_write_b32 v1, v18
	v_add_u32_e32 v1, 0x1d330, v0
	ds_write_b32 v1, v19
	v_add_u32_e32 v1, 0x1c740, v0
	ds_write_b32 v1, v12
	v_add_u32_e32 v1, 0x1cb50, v0
	ds_write_b32 v1, v13
	v_add_u32_e32 v1, 0x1cf60, v0
	ds_write_b32 v1, v14
	v_add_u32_e32 v1, 0x1d370, v0
	ds_write_b32 v1, v15
	v_add_u32_e32 v1, 0x1c780, v0
	ds_write_b32 v1, v8
	v_add_u32_e32 v1, 0x1cb90, v0
	ds_write_b32 v1, v9
	v_add_u32_e32 v1, 0x1cfa0, v0
	ds_write_b32 v1, v10
	v_add_u32_e32 v1, 0x1d3b0, v0
	ds_write_b32 v1, v11
	v_add_u32_e32 v1, 0x1c7c0, v0
	ds_write_b32 v1, v4
	v_add_u32_e32 v1, 0x1cbd0, v0
	ds_write_b32 v1, v5
	v_add_u32_e32 v1, 0x1cfe0, v0
	v_add_u32_e32 v0, 0x1d3f0, v0
	ds_write_b32 v1, v6
	ds_write_b32 v0, v7
	s_branch .LBB0_2109

; DI int TID512() { int t = threadIdx.x; asm volatile("" : "+v"(t)); return t; }
; template <bool ADD>
; DI void imgf_store(float* dst, const float* rsrc, int ld, const char* smem) {
;   const int tid = TID512();
;   const unsigned o0 = (unsigned)((tid >> 6) * ld + (tid & 63) * 4);
;   const char* src = smem + (tid >> 6) * (IMGF_LD * 4) + (tid & 63) * 16;
; #pragma unroll
;   for (int q = 0; q < 16; ++q) {
;     if ((q & 3) == 0) asm volatile("" ::: "memory");
;     float4 v = *(const float4*)(src + q * 8 * (IMGF_LD * 4));
;     float4* d = (float4*)(dst + (o0 + (unsigned)(q * 8 * ld)));
;     if (ADD) { const f32x4 x = __builtin_nontemporal_load((const f32x4*)(rsrc + (o0 + (unsigned)(q * 8 * ld)))); v.x += x[0]; v.y += x[1]; v.z += x[2]; v.w += x[3]; }
;     if (ADD) *d = v;
;     else __builtin_nontemporal_store(f32x4{v.x, v.y, v.z, v.w}, (f32x4*)d);
;   }
.LBB0_2581:
	s_or_b64 exec, exec, s[8:9]
	v_mov_b32_e32 v0, v184
	s_waitcnt lgkmcnt(0)
	s_barrier
	s_lshl_b32 s20, s20, 17
	s_xor_b64 s[8:9], s[12:13], -1
	s_lshl_b64 s[12:13], s[20:21], 2
	v_ashrrev_i32_e32 v1, 6, v0
	v_and_b32_e32 v0, 63, v0
	s_add_u32 s12, s5, s12
	v_lshlrev_b32_e32 v2, 2, v0
	s_addc_u32 s13, s7, s13
	v_lshl_or_b32 v172, v1, 10, v2
	v_lshl_add_u64 v[140:141], v[172:173], 2, s[12:13]
	v_mul_lo_u32 v1, v1, s71
	v_lshlrev_b32_e32 v0, 4, v0
	v_add3_u32 v0, 16, v1, v0
	v_add_u32_e32 v1, 0x10400, v0
	s_mov_b64 s[24:25], 0x8000
	ds_read_b128 v[230:233], v0
	ds_read_b128 v[234:237], v0 offset:8320
	ds_read_b128 v[238:241], v0 offset:16640
	ds_read_b128 v[242:245], v0 offset:24960
	s_waitcnt vmcnt(15) lgkmcnt(3)
	v_pk_add_f32 v[144:145], v[230:231], v[144:145]
	v_pk_add_f32 v[146:147], v[232:233], v[146:147]
	global_store_dwordx4 v[140:141], v[144:147], off
	v_lshl_add_u64 v[140:141], v[140:141], 0, s[24:25]
	ds_read_b128 v[230:233], v0 offset:33280
	s_waitcnt vmcnt(15) lgkmcnt(3)
	v_pk_add_f32 v[148:149], v[234:235], v[148:149]
	v_pk_add_f32 v[150:151], v[236:237], v[150:151]
	global_store_dwordx4 v[140:141], v[148:151], off
	v_lshl_add_u64 v[140:141], v[140:141], 0, s[24:25]
	ds_read_b128 v[234:237], v0 offset:41600
	s_waitcnt vmcnt(15) lgkmcnt(3)
	v_pk_add_f32 v[152:153], v[238:239], v[152:153]
	v_pk_add_f32 v[154:155], v[240:241], v[154:155]
	global_store_dwordx4 v[140:141], v[152:155], off
	v_lshl_add_u64 v[140:141], v[140:141], 0, s[24:25]
	ds_read_b128 v[238:241], v0 offset:49920
	s_waitcnt vmcnt(15) lgkmcnt(3)
	v_pk_add_f32 v[156:157], v[242:243], v[156:157]
	v_pk_add_f32 v[158:159], v[244:245], v[158:159]
	global_store_dwordx4 v[140:141], v[156:159], off
	v_lshl_add_u64 v[140:141], v[140:141], 0, s[24:25]
	ds_read_b128 v[242:245], v0 offset:58240
	s_waitcnt vmcnt(15) lgkmcnt(3)
	v_pk_add_f32 v[160:161], v[230:231], v[160:161]
	v_pk_add_f32 v[162:163], v[232:233], v[162:163]
	global_store_dwordx4 v[140:141], v[160:163], off
	v_lshl_add_u64 v[140:141], v[140:141], 0, s[24:25]
	ds_read_b128 v[230:233], v1
	s_waitcnt vmcnt(15) lgkmcnt(3)
	v_pk_add_f32 v[164:165], v[234:235], v[164:165]
	v_pk_add_f32 v[166:167], v[236:237], v[166:167]
	global_store_dwordx4 v[140:141], v[164:167], off
	v_lshl_add_u64 v[140:141], v[140:141], 0, s[24:25]
	ds_read_b128 v[234:237], v1 offset:8320
	s_waitcnt vmcnt(15) lgkmcnt(3)
	v_pk_add_f32 v[168:169], v[238:239], v[168:169]
	v_pk_add_f32 v[170:171], v[240:241], v[170:171]
	global_store_dwordx4 v[140:141], v[168:171], off
	v_lshl_add_u64 v[140:141], v[140:141], 0, s[24:25]
	ds_read_b128 v[238:241], v1 offset:16640
	s_waitcnt vmcnt(15) lgkmcnt(3)
	v_pk_add_f32 v[176:177], v[242:243], v[176:177]
	v_pk_add_f32 v[178:179], v[244:245], v[178:179]
	global_store_dwordx4 v[140:141], v[176:179], off
	v_lshl_add_u64 v[140:141], v[140:141], 0, s[24:25]
	ds_read_b128 v[242:245], v1 offset:24960
	s_waitcnt vmcnt(15) lgkmcnt(3)
	v_pk_add_f32 v[180:181], v[230:231], v[180:181]
	v_pk_add_f32 v[182:183], v[232:233], v[182:183]
	global_store_dwordx4 v[140:141], v[180:183], off
	v_lshl_add_u64 v[140:141], v[140:141], 0, s[24:25]
	ds_read_b128 v[230:233], v1 offset:33280
	s_waitcnt vmcnt(15) lgkmcnt(3)
	v_pk_add_f32 v[198:199], v[234:235], v[198:199]
	v_pk_add_f32 v[200:201], v[236:237], v[200:201]
	global_store_dwordx4 v[140:141], v[198:201], off
	v_lshl_add_u64 v[140:141], v[140:141], 0, s[24:25]
	ds_read_b128 v[234:237], v1 offset:41600
	s_waitcnt vmcnt(15) lgkmcnt(3)
	v_pk_add_f32 v[202:203], v[238:239], v[202:203]
	v_pk_add_f32 v[204:205], v[240:241], v[204:205]
	global_store_dwordx4 v[140:141], v[202:205], off
	v_lshl_add_u64 v[140:141], v[140:141], 0, s[24:25]
	ds_read_b128 v[238:241], v1 offset:49920
	s_waitcnt vmcnt(15) lgkmcnt(3)
	v_pk_add_f32 v[206:207], v[242:243], v[206:207]
	v_pk_add_f32 v[208:209], v[244:245], v[208:209]
	global_store_dwordx4 v[140:141], v[206:209], off
	v_lshl_add_u64 v[140:141], v[140:141], 0, s[24:25]
	ds_read_b128 v[242:245], v1 offset:58240
	s_waitcnt vmcnt(15) lgkmcnt(3)
	v_pk_add_f32 v[214:215], v[230:231], v[214:215]
	v_pk_add_f32 v[216:217], v[232:233], v[216:217]
	global_store_dwordx4 v[140:141], v[214:217], off
	v_lshl_add_u64 v[140:141], v[140:141], 0, s[24:25]
	s_waitcnt vmcnt(15) lgkmcnt(2)
	v_pk_add_f32 v[218:219], v[234:235], v[218:219]
	v_pk_add_f32 v[220:221], v[236:237], v[220:221]
	global_store_dwordx4 v[140:141], v[218:221], off
	v_lshl_add_u64 v[140:141], v[140:141], 0, s[24:25]
	s_waitcnt vmcnt(15) lgkmcnt(1)
	v_pk_add_f32 v[222:223], v[238:239], v[222:223]
	v_pk_add_f32 v[224:225], v[240:241], v[224:225]
	global_store_dwordx4 v[140:141], v[222:225], off
	v_lshl_add_u64 v[140:141], v[140:141], 0, s[24:25]
	s_waitcnt vmcnt(15) lgkmcnt(0)
	v_pk_add_f32 v[226:227], v[242:243], v[226:227]
	v_pk_add_f32 v[228:229], v[244:245], v[228:229]
	global_store_dwordx4 v[140:141], v[226:229], off
	s_mov_b32 s20, 1
	s_and_b64 vcc, exec, s[8:9]
	s_mov_b64 s[12:13], 0
	s_cbranch_vccnz .LBB0_2584
; DI void img_barrier() { asm volatile("s_waitcnt lgkmcnt(0)" ::: "memory"); __builtin_amdgcn_s_barrier(); }
; template <bool ADD>
; DI void imgf_store(float* dst, const float* rsrc, int ld, const char* smem) {
;     ...
;     float4 v = *(const float4*)(src + q * 8 * (IMGF_LD * 4));
;     float4* d = (float4*)(dst + (o0 + (unsigned)(q * 8 * ld)));
;     if (ADD) { const f32x4 x = __builtin_nontemporal_load((const f32x4*)(rsrc + (o0 + (unsigned)(q * 8 * ld)))); v.x += x[0]; v.y += x[1]; v.z += x[2]; v.w += x[3]; }
; template <bool ADD, bool ROPE>
; DI void tile_out_f32(const f32x4 (&acc)[8][4], float* dst, int ld, char* smem, int prow0, const float* cosT, const float* rsrc = nullptr) {
; #pragma unroll 1
;   for (int h = 0; h < 2; ++h) {
;     img_barrier();
;     imgf_put<ROPE>(acc, h, smem, prow0, cosT);
;     img_barrier();
;     imgf_store<ADD>(dst + (size_t)h * 128 * ld, ADD ? rsrc + (size_t)h * 128 * ld : nullptr, ld, smem);
.LBB0_2582:
	s_waitcnt lgkmcnt(0)
	v_mov_b32_e32 v0, v184
	s_barrier
	s_lshl_b32 s34, s20, 19
	s_add_u32 s48, s5, s34
	s_addc_u32 s49, s7, 0
	v_ashrrev_i32_e32 v134, 6, v184
	v_and_b32_e32 v135, 63, v184
	v_lshlrev_b32_e32 v135, 2, v135
	v_lshl_or_b32 v172, v134, 10, v135
	v_lshl_add_u64 v[132:133], v[172:173], 2, s[48:49]
	s_mov_b64 s[24:25], 0x8000
	global_load_dwordx4 v[144:147], v[132:133], off nt
	v_lshl_add_u64 v[132:133], v[132:133], 0, s[24:25]
	global_load_dwordx4 v[148:151], v[132:133], off nt
	v_lshl_add_u64 v[132:133], v[132:133], 0, s[24:25]
	global_load_dwordx4 v[152:155], v[132:133], off nt
	v_lshl_add_u64 v[132:133], v[132:133], 0, s[24:25]
	global_load_dwordx4 v[156:159], v[132:133], off nt
	v_lshl_add_u64 v[132:133], v[132:133], 0, s[24:25]
	global_load_dwordx4 v[160:163], v[132:133], off nt
	v_lshl_add_u64 v[132:133], v[132:133], 0, s[24:25]
	global_load_dwordx4 v[164:167], v[132:133], off nt
	v_lshl_add_u64 v[132:133], v[132:133], 0, s[24:25]
	global_load_dwordx4 v[168:171], v[132:133], off nt
	v_lshl_add_u64 v[132:133], v[132:133], 0, s[24:25]
	global_load_dwordx4 v[176:179], v[132:133], off nt
	v_lshl_add_u64 v[132:133], v[132:133], 0, s[24:25]
	global_load_dwordx4 v[180:183], v[132:133], off nt
	v_lshl_add_u64 v[132:133], v[132:133], 0, s[24:25]
	global_load_dwordx4 v[198:201], v[132:133], off nt
	v_lshl_add_u64 v[132:133], v[132:133], 0, s[24:25]
	global_load_dwordx4 v[202:205], v[132:133], off nt
	v_lshl_add_u64 v[132:133], v[132:133], 0, s[24:25]
	global_load_dwordx4 v[206:209], v[132:133], off nt
	v_lshl_add_u64 v[132:133], v[132:133], 0, s[24:25]
	global_load_dwordx4 v[214:217], v[132:133], off nt
	v_lshl_add_u64 v[132:133], v[132:133], 0, s[24:25]
	global_load_dwordx4 v[218:221], v[132:133], off nt
	v_lshl_add_u64 v[132:133], v[132:133], 0, s[24:25]
	global_load_dwordx4 v[222:225], v[132:133], off nt
	v_lshl_add_u64 v[132:133], v[132:133], 0, s[24:25]
	global_load_dwordx4 v[226:229], v[132:133], off nt
	s_nop 0
	v_ashrrev_i32_e32 v1, 8, v0
	v_cmp_eq_u32_e32 vcc, s20, v1
	s_and_saveexec_b64 s[8:9], vcc
	s_cbranch_execz .LBB0_2581
; template <bool ROPE>
; DI void imgf_put(const f32x4 (&acc)[8][4], int h, char* smem, int prow0, const float* cosT) {
;     ...
;   if (wr == h) {
;     float* f = (float*)smem + (fq * 4) * IMGF_LD + wc * 64 + fr;
; #pragma unroll
;     for (int m = 0; m < 8; ++m) {
;       float cs4[4] = {0.f, 0.f, 0.f, 0.f}, sn4[4] = {0.f, 0.f, 0.f, 0.f};
;       if (ROPE) {
; #pragma unroll
;         for (int j = 0; j < 4; ++j) { const int pos = prow0 + wr * 128 + m * 16 + fq * 4 + j; cs4[j] = cosT[pos * 8 + (fr & 7)]; sn4[j] = cosT[8192 * 8 + pos * 8 + (fr & 7)]; }
;       }
; #pragma unroll
;       for (int n = 0; n < 4; ++n)
; #pragma unroll
;         for (int j = 0; j < 4; ++j) f[(m * 16 + j) * IMGF_LD + n * 16] = epi_val<ROPE>(acc, m, n, j, cs4, sn4, fr);
;     }
	v_and_b32_e32 v1, 15, v0
	v_and_b32_e32 v2, 0xc0, v0
	v_lshrrev_b32_e32 v0, 2, v0
	v_and_b32_e32 v0, 12, v0
	v_mad_u32_u24 v0, v0, s71, 16
	v_lshlrev_b32_e32 v2, 2, v2
	v_lshlrev_b32_e32 v1, 2, v1
	v_add3_u32 v0, v0, v2, v1
	v_add_u32_e32 v1, 0x400, v0
	v_add_u32_e32 v2, 0x800, v0
	v_add_u32_e32 v132, 0xc00, v0
	ds_write2_b32 v0, v128, v124 offset1:16
	ds_write2_b32 v1, v129, v125 offset0:4 offset1:20
	ds_write2_b32 v2, v130, v126 offset0:8 offset1:24
	ds_write2_b32 v132, v131, v127 offset0:12 offset1:28
	ds_write2_b32 v0, v120, v116 offset0:32 offset1:48
	ds_write2_b32 v1, v121, v117 offset0:36 offset1:52
	ds_write2_b32 v2, v122, v118 offset0:40 offset1:56
	ds_write2_b32 v132, v123, v119 offset0:44 offset1:60
	v_add_u32_e32 v1, 0x4000, v0
	v_add_u32_e32 v2, 0x4400, v0
	v_add_u32_e32 v132, 0x4800, v0
	v_add_u32_e32 v133, 0x4c00, v0
	ds_write2_b32 v1, v112, v108 offset0:64 offset1:80
	ds_write2_b32 v2, v113, v109 offset0:68 offset1:84
	ds_write2_b32 v132, v114, v110 offset0:72 offset1:88
	ds_write2_b32 v133, v115, v111 offset0:76 offset1:92
	ds_write2_b32 v1, v104, v100 offset0:96 offset1:112
	ds_write2_b32 v2, v105, v101 offset0:100 offset1:116
	ds_write2_b32 v132, v106, v102 offset0:104 offset1:120
	ds_write2_b32 v133, v107, v103 offset0:108 offset1:124
	v_add_u32_e32 v1, 0x8000, v0
	v_add_u32_e32 v2, 0x8400, v0
	v_add_u32_e32 v132, 0x8800, v0
	v_add_u32_e32 v133, 0x8c00, v0
	ds_write2_b32 v1, v96, v92 offset0:128 offset1:144
	ds_write2_b32 v2, v97, v93 offset0:132 offset1:148
	ds_write2_b32 v132, v98, v94 offset0:136 offset1:152
	ds_write2_b32 v133, v99, v95 offset0:140 offset1:156
	ds_write2_b32 v1, v88, v84 offset0:160 offset1:176
	ds_write2_b32 v2, v89, v85 offset0:164 offset1:180
	ds_write2_b32 v132, v90, v86 offset0:168 offset1:184
	ds_write2_b32 v133, v91, v87 offset0:172 offset1:188
	v_add_u32_e32 v1, 0xc000, v0
	v_add_u32_e32 v2, 0xc400, v0
	v_add_u32_e32 v132, 0xc800, v0
	v_add_u32_e32 v133, 0xcc00, v0
	ds_write2_b32 v1, v80, v76 offset0:192 offset1:208
	ds_write2_b32 v2, v81, v77 offset0:196 offset1:212
	ds_write2_b32 v132, v82, v78 offset0:200 offset1:216
	ds_write2_b32 v133, v83, v79 offset0:204 offset1:220
	ds_write2_b32 v1, v72, v68 offset0:224 offset1:240
	ds_write2_b32 v2, v73, v69 offset0:228 offset1:244
	ds_write2_b32 v132, v74, v70 offset0:232 offset1:248
	ds_write2_b32 v133, v75, v71 offset0:236 offset1:252
	v_add_u32_e32 v1, 0x10400, v0
	ds_write_b32 v1, v64
	v_add_u32_e32 v1, 0x10810, v0
	ds_write_b32 v1, v65
	v_add_u32_e32 v1, 0x10c20, v0
	ds_write_b32 v1, v66
	v_add_u32_e32 v1, 0x11030, v0
	ds_write_b32 v1, v67
	v_add_u32_e32 v1, 0x10440, v0
	ds_write_b32 v1, v60
	v_add_u32_e32 v1, 0x10850, v0
	ds_write_b32 v1, v61
	v_add_u32_e32 v1, 0x10c60, v0
	ds_write_b32 v1, v62
	v_add_u32_e32 v1, 0x11070, v0
	ds_write_b32 v1, v63
	v_add_u32_e32 v1, 0x10480, v0
	ds_write_b32 v1, v56
	v_add_u32_e32 v1, 0x10890, v0
	ds_write_b32 v1, v57
	v_add_u32_e32 v1, 0x10ca0, v0
	ds_write_b32 v1, v58
	v_add_u32_e32 v1, 0x110b0, v0
	ds_write_b32 v1, v59
	v_add_u32_e32 v1, 0x104c0, v0
	ds_write_b32 v1, v52
	v_add_u32_e32 v1, 0x108d0, v0
	ds_write_b32 v1, v53
	v_add_u32_e32 v1, 0x10ce0, v0
	ds_write_b32 v1, v54
	v_add_u32_e32 v1, 0x110f0, v0
	ds_write_b32 v1, v55
	v_add_u32_e32 v1, 0x14500, v0
	ds_write_b32 v1, v48
	v_add_u32_e32 v1, 0x14910, v0
	ds_write_b32 v1, v49
	v_add_u32_e32 v1, 0x14d20, v0
	ds_write_b32 v1, v50
	v_add_u32_e32 v1, 0x15130, v0
	ds_write_b32 v1, v51
	v_add_u32_e32 v1, 0x14540, v0
	ds_write_b32 v1, v44
	v_add_u32_e32 v1, 0x14950, v0
	ds_write_b32 v1, v45
	v_add_u32_e32 v1, 0x14d60, v0
	ds_write_b32 v1, v46
	v_add_u32_e32 v1, 0x15170, v0
	ds_write_b32 v1, v47
	v_add_u32_e32 v1, 0x14580, v0
	ds_write_b32 v1, v40
	v_add_u32_e32 v1, 0x14990, v0
	ds_write_b32 v1, v41
	v_add_u32_e32 v1, 0x14da0, v0
	ds_write_b32 v1, v42
	v_add_u32_e32 v1, 0x151b0, v0
	ds_write_b32 v1, v43
	v_add_u32_e32 v1, 0x145c0, v0
	ds_write_b32 v1, v36
	v_add_u32_e32 v1, 0x149d0, v0
	ds_write_b32 v1, v37
	v_add_u32_e32 v1, 0x14de0, v0
	ds_write_b32 v1, v38
	v_add_u32_e32 v1, 0x151f0, v0
	ds_write_b32 v1, v39
	v_add_u32_e32 v1, 0x18600, v0
	ds_write_b32 v1, v32
	v_add_u32_e32 v1, 0x18a10, v0
	ds_write_b32 v1, v33
	v_add_u32_e32 v1, 0x18e20, v0
	ds_write_b32 v1, v34
	v_add_u32_e32 v1, 0x19230, v0
	ds_write_b32 v1, v35
	v_add_u32_e32 v1, 0x18640, v0
	ds_write_b32 v1, v28
	v_add_u32_e32 v1, 0x18a50, v0
	ds_write_b32 v1, v29
	v_add_u32_e32 v1, 0x18e60, v0
	ds_write_b32 v1, v30
	v_add_u32_e32 v1, 0x19270, v0
	ds_write_b32 v1, v31
	v_add_u32_e32 v1, 0x18680, v0
	ds_write_b32 v1, v24
	v_add_u32_e32 v1, 0x18a90, v0
	ds_write_b32 v1, v25
	v_add_u32_e32 v1, 0x18ea0, v0
	ds_write_b32 v1, v26
	v_add_u32_e32 v1, 0x192b0, v0
	ds_write_b32 v1, v27
	v_add_u32_e32 v1, 0x186c0, v0
	ds_write_b32 v1, v20
	v_add_u32_e32 v1, 0x18ad0, v0
	ds_write_b32 v1, v21
	v_add_u32_e32 v1, 0x18ee0, v0
	ds_write_b32 v1, v22
	v_add_u32_e32 v1, 0x192f0, v0
	ds_write_b32 v1, v23
	v_add_u32_e32 v1, 0x1c700, v0
	ds_write_b32 v1, v16
	v_add_u32_e32 v1, 0x1cb10, v0
	ds_write_b32 v1, v17
	v_add_u32_e32 v1, 0x1cf20, v0
	ds_write_b32 v1, v18
	v_add_u32_e32 v1, 0x1d330, v0
	ds_write_b32 v1, v19
	v_add_u32_e32 v1, 0x1c740, v0
	ds_write_b32 v1, v12
	v_add_u32_e32 v1, 0x1cb50, v0
	ds_write_b32 v1, v13
	v_add_u32_e32 v1, 0x1cf60, v0
	ds_write_b32 v1, v14
	v_add_u32_e32 v1, 0x1d370, v0
	ds_write_b32 v1, v15
	v_add_u32_e32 v1, 0x1c780, v0
	ds_write_b32 v1, v8
	v_add_u32_e32 v1, 0x1cb90, v0
	ds_write_b32 v1, v9
	v_add_u32_e32 v1, 0x1cfa0, v0
	ds_write_b32 v1, v10
	v_add_u32_e32 v1, 0x1d3b0, v0
	ds_write_b32 v1, v11
	v_add_u32_e32 v1, 0x1c7c0, v0
	ds_write_b32 v1, v4
	v_add_u32_e32 v1, 0x1cbd0, v0
	ds_write_b32 v1, v5
	v_add_u32_e32 v1, 0x1cfe0, v0
	v_add_u32_e32 v0, 0x1d3f0, v0
	ds_write_b32 v1, v6
	ds_write_b32 v0, v7
	s_branch .LBB0_2581
